# MLA attention rewritten on v_mfma_f32_16x16x32_bf16 (same bf16-in f32-acc numerics; key-row permuted QK tiles feed P.V with no lane movement; reference max in the accumulator init with lazy 2^8 rescal
# speedup vs baseline: 1.1293x; 1.0545x over previous
.LBB0_761:
	v_add_u32_e32 v238, v209, v200
	ds_read_b128 v[218:221], v238
	ds_read_b128 v[222:225], v238 offset:2304
	ds_read_b128 v[226:229], v238 offset:4608
	ds_read_b128 v[230:233], v238 offset:6912
	s_waitcnt lgkmcnt(3)
	v_mfma_f32_16x16x32_bf16 v[2:5], v[218:221], v[150:153], v[2:5]
	v_mfma_f32_16x16x32_bf16 v[6:9], v[218:221], v[154:157], v[6:9]
	ds_read_b128 v[234:237], v238 offset:9216
	s_waitcnt lgkmcnt(3)
	v_mfma_f32_16x16x32_bf16 v[10:13], v[222:225], v[150:153], v[10:13]
	v_mfma_f32_16x16x32_bf16 v[14:17], v[222:225], v[154:157], v[14:17]
	ds_read_b128 v[218:221], v238 offset:11520
	s_waitcnt lgkmcnt(3)
	v_mfma_f32_16x16x32_bf16 v[18:21], v[226:229], v[150:153], v[18:21]
	v_mfma_f32_16x16x32_bf16 v[22:25], v[226:229], v[154:157], v[22:25]
	ds_read_b128 v[222:225], v238 offset:13824
	s_waitcnt lgkmcnt(3)
	v_mfma_f32_16x16x32_bf16 v[26:29], v[230:233], v[150:153], v[26:29]
	v_mfma_f32_16x16x32_bf16 v[30:33], v[230:233], v[154:157], v[30:33]
	ds_read_b128 v[226:229], v238 offset:16128
	s_waitcnt lgkmcnt(3)
	v_mfma_f32_16x16x32_bf16 v[34:37], v[234:237], v[150:153], v[34:37]
	v_mfma_f32_16x16x32_bf16 v[38:41], v[234:237], v[154:157], v[38:41]
	s_waitcnt lgkmcnt(2)
	v_mfma_f32_16x16x32_bf16 v[42:45], v[218:221], v[150:153], v[42:45]
	v_mfma_f32_16x16x32_bf16 v[46:49], v[218:221], v[154:157], v[46:49]
	s_waitcnt lgkmcnt(1)
	v_mfma_f32_16x16x32_bf16 v[50:53], v[222:225], v[150:153], v[50:53]
	v_mfma_f32_16x16x32_bf16 v[54:57], v[222:225], v[154:157], v[54:57]
	s_waitcnt lgkmcnt(0)
	v_mfma_f32_16x16x32_bf16 v[58:61], v[226:229], v[150:153], v[58:61]
	v_mfma_f32_16x16x32_bf16 v[62:65], v[226:229], v[154:157], v[62:65]
	ds_bpermute_b32 v245, v208, v199
	ds_bpermute_b32 v247, v208, v203
	s_waitcnt lgkmcnt(0)
	v_add_f32_e32 v199, v199, v245
	v_add_f32_e32 v203, v203, v247
	ds_bpermute_b32 v245, v198, v199
	ds_bpermute_b32 v247, v198, v203
	s_waitcnt lgkmcnt(0)
	v_add_f32_e32 v199, v199, v245
	v_add_f32_e32 v203, v203, v247
	s_barrier
	v_div_scale_f32 v66, s[6:7], v199, v199, 1.0
	v_rcp_f32_e32 v67, v66
	s_nop 0
	v_fma_f32 v68, -v66, v67, 1.0
	v_fmac_f32_e32 v67, v68, v67
	v_div_scale_f32 v68, vcc, 1.0, v199, 1.0
	v_mul_f32_e32 v69, v68, v67
	v_fma_f32 v70, -v66, v69, v68
	v_fmac_f32_e32 v69, v70, v67
	v_fma_f32 v66, -v66, v69, v68
	v_div_fmas_f32 v66, v66, v67, v69
	v_div_fixup_f32 v66, v66, v199, 1.0
	v_div_scale_f32 v74, s[6:7], v203, v203, 1.0
	v_rcp_f32_e32 v75, v74
	s_nop 0
	v_fma_f32 v76, -v74, v75, 1.0
	v_fmac_f32_e32 v75, v76, v75
	v_div_scale_f32 v76, vcc, 1.0, v203, 1.0
	v_mul_f32_e32 v77, v76, v75
	v_fma_f32 v78, -v74, v77, v76
	v_fmac_f32_e32 v77, v78, v75
	v_fma_f32 v74, -v74, v77, v76
	v_div_fmas_f32 v74, v74, v75, v77
	v_div_fixup_f32 v74, v74, v203, 1.0
	s_lshl_b32 s4, s86, 8
	s_add_u32 s4, s75, s4
	s_addc_u32 s5, s76, 0
	v_ashrrev_i32_e32 v159, 31, v158
	v_lshlrev_b64 v[238:239], 11, v[158:159]
	v_lshl_add_u64 v[238:239], s[4:5], 0, v[238:239]
	v_bfe_u32 v0, v162, 4, 2
	v_lshlrev_b32_e32 v0, 3, v0
	v_lshl_add_u64 v[238:239], v[238:239], 0, v[0:1]
	v_add_co_u32_e32 v244, vcc, 0x8000, v238
	s_nop 1
	v_addc_co_u32_e32 v245, vcc, 0, v239, vcc
	v_mul_f32_e32 v2, v2, v66
	v_mul_f32_e32 v3, v3, v66
	v_mul_f32_e32 v4, v4, v66
	v_mul_f32_e32 v5, v5, v66
	v_cvt_pk_bf16_f32 v240, v2, v3
	v_cvt_pk_bf16_f32 v241, v4, v5
	global_store_dwordx2 v[238:239], v[240:241], off
	v_mul_f32_e32 v6, v6, v74
	v_mul_f32_e32 v7, v7, v74
	v_mul_f32_e32 v8, v8, v74
	v_mul_f32_e32 v9, v9, v74
	v_cvt_pk_bf16_f32 v242, v6, v7
	v_cvt_pk_bf16_f32 v243, v8, v9
	global_store_dwordx2 v[244:245], v[242:243], off
	v_mul_f32_e32 v10, v10, v66
	v_mul_f32_e32 v11, v11, v66
	v_mul_f32_e32 v12, v12, v66
	v_mul_f32_e32 v13, v13, v66
	v_cvt_pk_bf16_f32 v240, v10, v11
	v_cvt_pk_bf16_f32 v241, v12, v13
	global_store_dwordx2 v[238:239], v[240:241], off offset:32
	v_mul_f32_e32 v14, v14, v74
	v_mul_f32_e32 v15, v15, v74
	v_mul_f32_e32 v16, v16, v74
	v_mul_f32_e32 v17, v17, v74
	v_cvt_pk_bf16_f32 v242, v14, v15
	v_cvt_pk_bf16_f32 v243, v16, v17
	global_store_dwordx2 v[244:245], v[242:243], off offset:32
	v_mul_f32_e32 v18, v18, v66
	v_mul_f32_e32 v19, v19, v66
	v_mul_f32_e32 v20, v20, v66
	v_mul_f32_e32 v21, v21, v66
	v_cvt_pk_bf16_f32 v240, v18, v19
	v_cvt_pk_bf16_f32 v241, v20, v21
	global_store_dwordx2 v[238:239], v[240:241], off offset:64
	v_mul_f32_e32 v22, v22, v74
	v_mul_f32_e32 v23, v23, v74
	v_mul_f32_e32 v24, v24, v74
	v_mul_f32_e32 v25, v25, v74
	v_cvt_pk_bf16_f32 v242, v22, v23
	v_cvt_pk_bf16_f32 v243, v24, v25
	global_store_dwordx2 v[244:245], v[242:243], off offset:64
	v_mul_f32_e32 v26, v26, v66
	v_mul_f32_e32 v27, v27, v66
	v_mul_f32_e32 v28, v28, v66
	v_mul_f32_e32 v29, v29, v66
	v_cvt_pk_bf16_f32 v240, v26, v27
	v_cvt_pk_bf16_f32 v241, v28, v29
	global_store_dwordx2 v[238:239], v[240:241], off offset:96
	v_mul_f32_e32 v30, v30, v74
	v_mul_f32_e32 v31, v31, v74
	v_mul_f32_e32 v32, v32, v74
	v_mul_f32_e32 v33, v33, v74
	v_cvt_pk_bf16_f32 v242, v30, v31
	v_cvt_pk_bf16_f32 v243, v32, v33
	global_store_dwordx2 v[244:245], v[242:243], off offset:96
	v_mul_f32_e32 v34, v34, v66
	v_mul_f32_e32 v35, v35, v66
	v_mul_f32_e32 v36, v36, v66
	v_mul_f32_e32 v37, v37, v66
	v_cvt_pk_bf16_f32 v240, v34, v35
	v_cvt_pk_bf16_f32 v241, v36, v37
	global_store_dwordx2 v[238:239], v[240:241], off offset:128
	v_mul_f32_e32 v38, v38, v74
	v_mul_f32_e32 v39, v39, v74
	v_mul_f32_e32 v40, v40, v74
	v_mul_f32_e32 v41, v41, v74
	v_cvt_pk_bf16_f32 v242, v38, v39
	v_cvt_pk_bf16_f32 v243, v40, v41
	global_store_dwordx2 v[244:245], v[242:243], off offset:128
	v_mul_f32_e32 v42, v42, v66
	v_mul_f32_e32 v43, v43, v66
	v_mul_f32_e32 v44, v44, v66
	v_mul_f32_e32 v45, v45, v66
	v_cvt_pk_bf16_f32 v240, v42, v43
	v_cvt_pk_bf16_f32 v241, v44, v45
	global_store_dwordx2 v[238:239], v[240:241], off offset:160
	v_mul_f32_e32 v46, v46, v74
	v_mul_f32_e32 v47, v47, v74
	v_mul_f32_e32 v48, v48, v74
	v_mul_f32_e32 v49, v49, v74
	v_cvt_pk_bf16_f32 v242, v46, v47
	v_cvt_pk_bf16_f32 v243, v48, v49
	global_store_dwordx2 v[244:245], v[242:243], off offset:160
	v_mul_f32_e32 v50, v50, v66
	v_mul_f32_e32 v51, v51, v66
	v_mul_f32_e32 v52, v52, v66
	v_mul_f32_e32 v53, v53, v66
	v_cvt_pk_bf16_f32 v240, v50, v51
	v_cvt_pk_bf16_f32 v241, v52, v53
	global_store_dwordx2 v[238:239], v[240:241], off offset:192
	v_mul_f32_e32 v54, v54, v74
	v_mul_f32_e32 v55, v55, v74
	v_mul_f32_e32 v56, v56, v74
	v_mul_f32_e32 v57, v57, v74
	v_cvt_pk_bf16_f32 v242, v54, v55
	v_cvt_pk_bf16_f32 v243, v56, v57
	global_store_dwordx2 v[244:245], v[242:243], off offset:192
	v_mul_f32_e32 v58, v58, v66
	v_mul_f32_e32 v59, v59, v66
	v_mul_f32_e32 v60, v60, v66
	v_mul_f32_e32 v61, v61, v66
	v_cvt_pk_bf16_f32 v240, v58, v59
	v_cvt_pk_bf16_f32 v241, v60, v61
	global_store_dwordx2 v[238:239], v[240:241], off offset:224
	v_mul_f32_e32 v62, v62, v74
	v_mul_f32_e32 v63, v63, v74
	v_mul_f32_e32 v64, v64, v74
	v_mul_f32_e32 v65, v65, v74
	v_cvt_pk_bf16_f32 v242, v62, v63
	v_cvt_pk_bf16_f32 v243, v64, v65
	global_store_dwordx2 v[244:245], v[242:243], off offset:224

.LBB0_763:
	s_and_b32 s4, s77, 1
	s_add_i32 s5, s77, s4
	s_sub_i32 s4, 0, s4
	s_xor_b32 s4, s2, s4
	s_mul_i32 s5, s5, s30
	s_add_i32 s4, s5, s4
	s_cmpk_gt_i32 s4, 0x1ff
	s_cbranch_scc1 .LBB0_762
	s_and_b32 s86, s4, 7
	s_mul_i32 s5, s86, 0x180
	s_add_u32 s10, s40, s5
	s_addc_u32 s11, s60, 0
	s_mul_i32 s5, s86, 0x600000
	s_add_u32 s6, s61, s5
	s_addc_u32 s7, s72, 0
	s_lshl_b32 s5, s86, 22
	s_add_u32 s8, s73, s5
	v_mov_b32_e32 v22, v162
	s_addc_u32 s9, s74, 0
	s_lshl_b32 s4, s4, 5
	s_and_b32 s54, s4, 0xffffff00
	v_ashrrev_i32_e32 v0, 1, v22
	v_and_b32_e32 v0, 0xffffffe0, v0
	v_subrev_u32_e32 v38, s54, v0
	v_and_b32_e32 v36, 31, v22
	v_add_u32_e32 v186, 0x3f00, v38
	v_bfe_u32 v37, v22, 5, 1
	v_or_b32_e32 v158, v186, v36
	v_and_b32_e32 v4, 15, v22
	v_bfe_u32 v5, v22, 4, 2
	v_add_u32_e32 v158, v186, v4
	v_lshlrev_b32_e32 v0, 4, v5
	v_mov_b64_e32 v[2:3], s[10:11]
	v_mad_i64_i32 v[2:3], s[4:5], v158, s45, v[2:3]
	v_lshl_add_u64 v[2:3], v[2:3], 0, v[0:1]
	v_add_co_u32_e32 v4, vcc, 0xc000, v2
	s_nop 1
	v_addc_co_u32_e32 v5, vcc, 0, v3, vcc
	global_load_dwordx4 v[82:85], v[2:3], off
	global_load_dwordx4 v[86:89], v[2:3], off offset:64
	global_load_dwordx4 v[90:93], v[2:3], off offset:128
	global_load_dwordx4 v[94:97], v[2:3], off offset:192
	global_load_dwordx4 v[98:101], v[2:3], off offset:256
	global_load_dwordx4 v[102:105], v[2:3], off offset:320
	global_load_dwordx4 v[106:109], v[4:5], off
	global_load_dwordx4 v[110:113], v[4:5], off offset:64
	global_load_dwordx4 v[114:117], v[4:5], off offset:128
	global_load_dwordx4 v[118:121], v[4:5], off offset:192
	global_load_dwordx4 v[122:125], v[4:5], off offset:256
	global_load_dwordx4 v[126:129], v[4:5], off offset:320
	v_add_u32_e32 v24, 0x200, v22
	v_ashrrev_i32_e32 v25, 31, v24
	v_ashrrev_i32_e32 v23, 31, v22
	v_lshrrev_b32_e32 v18, 29, v25
	v_lshrrev_b32_e32 v12, 29, v23
	v_add_u32_e32 v20, v24, v18
	v_add_u32_e32 v14, v22, v12
	v_ashrrev_i32_e32 v32, 3, v20
	v_and_b32_e32 v20, -8, v20
	v_lshlrev_b64 v[166:167], 4, v[24:25]
	v_add_u32_e32 v26, 0x400, v22
	v_ashrrev_i32_e32 v28, 3, v14
	v_and_b32_e32 v14, -8, v14
	v_ashrrev_i32_e32 v33, 31, v32
	v_sub_u32_e32 v25, v24, v20
	v_lshlrev_b64 v[160:161], 4, v[22:23]
	v_ashrrev_i32_e32 v27, 31, v26
	v_ashrrev_i32_e32 v29, 31, v28
	v_sub_u32_e32 v23, v22, v14
	v_lshlrev_b64 v[174:175], 15, v[32:33]
	v_lshlrev_b32_e32 v176, 3, v25
	v_lshlrev_b64 v[168:169], 4, v[26:27]
	v_lshlrev_b64 v[170:171], 15, v[28:29]
	v_lshlrev_b32_e32 v172, 3, v23
	v_lshl_add_u64 v[18:19], s[8:9], 0, v[174:175]
	v_ashrrev_i32_e32 v177, 31, v176
	v_lshl_add_u64 v[2:3], s[6:7], 0, v[160:161]
	v_lshl_add_u64 v[6:7], s[6:7], 0, v[166:167]
	v_lshl_add_u64 v[10:11], s[6:7], 0, v[168:169]
	v_lshl_add_u64 v[12:13], s[8:9], 0, v[170:171]
	v_ashrrev_i32_e32 v173, 31, v172
	v_lshl_add_u64 v[34:35], v[176:177], 1, v[18:19]
	global_load_dwordx4 v[2:5], v[2:3], off
	s_nop 0
	global_load_dwordx4 v[6:9], v[6:7], off
	v_lshl_add_u64 v[30:31], v[172:173], 1, v[12:13]
	global_load_dwordx4 v[10:13], v[10:11], off
	s_nop 0
	global_load_dwordx4 v[14:17], v[30:31], off
	global_load_dwordx4 v[18:21], v[34:35], off
	s_sub_i32 s4, 0x4000, s54
	v_and_b32_e32 v27, 63, v22
	v_ashrrev_i32_e32 v159, 31, v158
	v_mul_hi_i32 v29, v22, s29
	v_lshrrev_b32_e32 v33, 31, v29
	v_ashrrev_i32_e32 v29, 2, v29
	v_add_u32_e32 v29, v29, v33
	v_mul_lo_u32 v187, v29, s48
	v_mul_lo_u32 v29, v29, 24
	v_sub_u32_e32 v22, v22, v29
	v_lshlrev_b32_e32 v188, 4, v22
	v_add3_u32 v22, s78, v187, v188
	s_waitcnt vmcnt(4)
	ds_write_b128 v22, v[2:5]
	v_mul_hi_i32 v2, v24, s29
	v_lshrrev_b32_e32 v3, 31, v2
	v_ashrrev_i32_e32 v2, 2, v2
	v_add_u32_e32 v2, v2, v3
	v_mul_lo_u32 v189, v2, s48
	v_mul_lo_u32 v2, v2, 24
	v_sub_u32_e32 v2, v24, v2
	v_lshlrev_b32_e32 v190, 4, v2
	v_add3_u32 v2, s78, v189, v190
	s_waitcnt vmcnt(3)
	ds_write_b128 v2, v[6:9]
	v_mul_hi_i32 v2, v26, s29
	v_lshrrev_b32_e32 v3, 31, v2
	v_ashrrev_i32_e32 v2, 2, v2
	v_add_u32_e32 v2, v2, v3
	v_mul_lo_u32 v191, v2, s48
	v_mul_lo_u32 v2, v2, 24
	v_sub_u32_e32 v2, v26, v2
	v_lshlrev_b32_e32 v192, 4, v2
	s_movk_i32 s5, 0x90
	v_add3_u32 v2, s78, v191, v192
	v_mul_lo_u32 v193, v28, s5
	v_lshlrev_b32_e32 v194, 4, v23
	s_waitcnt vmcnt(2)
	ds_write_b128 v2, v[10:13]
	v_add3_u32 v2, s78, v193, v194
	v_mul_lo_u32 v195, v32, s5
	v_lshlrev_b32_e32 v196, 4, v25
	s_add_u32 s10, s6, 0x6000
	s_waitcnt vmcnt(1)
	ds_write_b128 v2, v[14:17] offset:51200
	v_add3_u32 v2, s78, v195, v196
	s_addc_u32 s11, s7, 0
	s_waitcnt vmcnt(0)
	ds_write_b128 v2, v[18:21] offset:51200
	v_lshl_add_u64 v[2:3], s[10:11], 0, v[160:161]
	global_load_dwordx4 v[130:133], v[2:3], off
	v_lshl_add_u64 v[2:3], s[10:11], 0, v[166:167]
	global_load_dwordx4 v[134:137], v[2:3], off
	v_lshl_add_u64 v[2:3], s[10:11], 0, v[168:169]
	global_load_dwordx4 v[138:141], v[2:3], off
	global_load_dwordx4 v[142:145], v[30:31], off offset:128
	global_load_dwordx4 v[146:149], v[34:35], off offset:128
	s_movk_i32 s49, 0x90
	s_lshr_b32 s87, s4, 6
	v_mul_u32_u24_e32 v2, 0x190, v36
	v_add3_u32 v202, s78, v2, v0
	v_lshlrev_b32_e32 v2, 2, v27
	v_mov_b32_e32 v50, v1
	v_mov_b32_e32 v51, v1
	v_add_u32_e32 v201, 0x3f3f, v38
	v_add_u32_e32 v203, 0x3f1f, v38
	v_lshlrev_b32_e32 v197, 2, v37
	v_xor_b32_e32 v198, 0x80, v2
	v_mul_u32_u24_e32 v200, 0x90, v36
	v_mov_b32_e32 v52, v1
	v_mov_b32_e32 v53, v1
	v_mov_b32_e32 v54, v1
	v_mov_b32_e32 v55, v1
	v_mov_b32_e32 v56, v1
	v_mov_b32_e32 v57, v1
	v_mov_b32_e32 v58, v1
	v_mov_b32_e32 v59, v1
	v_mov_b32_e32 v60, v1
	v_mov_b32_e32 v61, v1
	v_mov_b32_e32 v62, v1
	v_mov_b32_e32 v63, v1
	v_mov_b32_e32 v64, v1
	v_mov_b32_e32 v65, v1
	v_readlane_b32 s5, v246, 59
	v_mov_b64_e32 v[34:35], v[50:51]
	v_mov_b64_e32 v[18:19], v[50:51]
	v_mov_b64_e32 v[2:3], v[50:51]
	s_mov_b32 s4, 0
	v_mov_b32_e32 v199, 0
	v_mov_b32_e32 v206, 0xf149f2ca
	v_mov_b32_e32 v209, s5
	v_mov_b32_e32 v154, 0
	v_mov_b32_e32 v155, 0
	v_mov_b32_e32 v156, 0
	v_mov_b32_e32 v157, 0
	v_mov_b32_e32 v150, 0
	v_mov_b32_e32 v151, 0
	v_mov_b32_e32 v152, 0
	v_mov_b32_e32 v153, 0
	v_mov_b64_e32 v[36:37], v[52:53]
	v_mov_b64_e32 v[38:39], v[54:55]
	v_mov_b64_e32 v[40:41], v[56:57]
	v_mov_b64_e32 v[42:43], v[58:59]
	v_mov_b64_e32 v[44:45], v[60:61]
	v_mov_b64_e32 v[46:47], v[62:63]
	v_mov_b64_e32 v[48:49], v[64:65]
	v_mov_b64_e32 v[20:21], v[52:53]
	v_mov_b64_e32 v[22:23], v[54:55]
	v_mov_b64_e32 v[24:25], v[56:57]
	v_mov_b64_e32 v[26:27], v[58:59]
	v_mov_b64_e32 v[28:29], v[60:61]
	v_mov_b64_e32 v[30:31], v[62:63]
	v_mov_b64_e32 v[32:33], v[64:65]
	v_mov_b64_e32 v[4:5], v[52:53]
	v_mov_b64_e32 v[6:7], v[54:55]
	v_mov_b64_e32 v[8:9], v[56:57]
	v_mov_b64_e32 v[10:11], v[58:59]
	v_mov_b64_e32 v[12:13], v[60:61]
	v_mov_b64_e32 v[14:15], v[62:63]
	v_mov_b64_e32 v[16:17], v[64:65]
	v_and_b32_e32 v239, 15, v162
	v_bfe_u32 v244, v162, 4, 2
	v_lshrrev_b32_e32 v245, 3, v239
	v_lshl_add_u32 v245, v245, 3, v239
	v_mul_u32_u24_e32 v245, 0x190, v245
	v_lshlrev_b32_e32 v205, 4, v244
	v_add3_u32 v202, s78, v245, v205
	v_mul_u32_u24_e32 v245, 0x90, v239
	v_add_u32_e32 v200, v245, v205
	v_lshrrev_b32_e32 v245, 1, v244
	v_lshlrev_b32_e32 v245, 3, v245
	v_lshl_add_u32 v245, v244, 2, v245
	v_sub_u32_e32 v197, v245, v239
	v_and_b32_e32 v245, 63, v162
	v_xor_b32_e32 v245, 16, v245
	v_lshlrev_b32_e32 v208, 2, v245
	v_mov_b32_e32 v206, 0
	v_mov_b32_e32 v201, 0
	v_mov_b32_e32 v203, 0
	s_mov_b32 s21, 0
	v_mov_b32_e32 v210, 0
	v_mov_b32_e32 v211, 0
	v_mov_b32_e32 v212, 0
	v_mov_b32_e32 v213, 0
	v_mov_b32_e32 v214, 0
	v_mov_b32_e32 v215, 0
	v_mov_b32_e32 v216, 0
	v_mov_b32_e32 v217, 0
	v_readfirstlane_b32 s12, v186
	s_waitcnt lgkmcnt(0)
	s_barrier
	s_and_b32 s5, s4, 1
	s_add_i32 s88, s4, 1
	s_cmp_ge_u32 s88, s87
	s_cbranch_scc1 .LBB0_766

.Lv3_h0:
	s_mov_b32 s91, s54
	s_add_i32 s13, s12, 63
	s_cmp_le_i32 s91, s13
	s_cbranch_scc0 .Lv3_h0_end
	v_mov_b32_e32 v205, v204
	v_add_u32_e32 v238, v209, v200
	s_add_i32 s4, s89, 0xc800
	ds_read_b128 v[218:221], v205
	ds_read_b128 v[222:225], v205 offset:3200
	ds_read_b128 v[226:229], v205 offset:64
	ds_read_b128 v[230:233], v205 offset:3264
	v_mov_b32_e32 v209, s4
	s_waitcnt lgkmcnt(3)
	v_mfma_f32_16x16x32_bf16 v[66:69], v[218:221], v[82:85], v[210:213]
	v_mfma_f32_16x16x32_bf16 v[70:73], v[218:221], v[106:109], v[214:217]
	ds_read_b128 v[234:237], v205 offset:128
	s_waitcnt lgkmcnt(3)
	v_mfma_f32_16x16x32_bf16 v[74:77], v[222:225], v[82:85], v[210:213]
	v_mfma_f32_16x16x32_bf16 v[78:81], v[222:225], v[106:109], v[214:217]
	ds_read_b128 v[218:221], v205 offset:3328
	s_waitcnt lgkmcnt(3)
	v_mfma_f32_16x16x32_bf16 v[66:69], v[226:229], v[86:89], v[66:69]
	v_mfma_f32_16x16x32_bf16 v[70:73], v[226:229], v[110:113], v[70:73]
	ds_read_b128 v[222:225], v205 offset:192
	s_waitcnt lgkmcnt(3)
	v_mfma_f32_16x16x32_bf16 v[74:77], v[230:233], v[86:89], v[74:77]
	v_mfma_f32_16x16x32_bf16 v[78:81], v[230:233], v[110:113], v[78:81]
	ds_read_b128 v[226:229], v205 offset:3392
	s_waitcnt lgkmcnt(3)
	v_mfma_f32_16x16x32_bf16 v[66:69], v[234:237], v[90:93], v[66:69]
	v_mfma_f32_16x16x32_bf16 v[70:73], v[234:237], v[114:117], v[70:73]
	ds_read_b128 v[230:233], v205 offset:256
	s_waitcnt lgkmcnt(3)
	v_mfma_f32_16x16x32_bf16 v[74:77], v[218:221], v[90:93], v[74:77]
	v_mfma_f32_16x16x32_bf16 v[78:81], v[218:221], v[114:117], v[78:81]
	ds_read_b128 v[234:237], v205 offset:3456
	s_waitcnt lgkmcnt(3)
	v_mfma_f32_16x16x32_bf16 v[66:69], v[222:225], v[94:97], v[66:69]
	v_mfma_f32_16x16x32_bf16 v[70:73], v[222:225], v[118:121], v[70:73]
	ds_read_b128 v[218:221], v205 offset:320
	s_waitcnt lgkmcnt(3)
	v_mfma_f32_16x16x32_bf16 v[74:77], v[226:229], v[94:97], v[74:77]
	v_mfma_f32_16x16x32_bf16 v[78:81], v[226:229], v[118:121], v[78:81]
	ds_read_b128 v[222:225], v205 offset:3520
	s_waitcnt lgkmcnt(3)
	v_mfma_f32_16x16x32_bf16 v[66:69], v[230:233], v[98:101], v[66:69]
	v_mfma_f32_16x16x32_bf16 v[70:73], v[230:233], v[122:125], v[70:73]
	ds_read_b128 v[226:229], v238
	s_waitcnt lgkmcnt(3)
	v_mfma_f32_16x16x32_bf16 v[74:77], v[234:237], v[98:101], v[74:77]
	v_mfma_f32_16x16x32_bf16 v[78:81], v[234:237], v[122:125], v[78:81]
	ds_read_b128 v[230:233], v238 offset:2304
	s_waitcnt lgkmcnt(3)
	v_mfma_f32_16x16x32_bf16 v[66:69], v[218:221], v[102:105], v[66:69]
	v_mfma_f32_16x16x32_bf16 v[70:73], v[218:221], v[126:129], v[70:73]
	ds_read_b128 v[234:237], v238 offset:4608
	s_waitcnt lgkmcnt(3)
	v_mfma_f32_16x16x32_bf16 v[74:77], v[222:225], v[102:105], v[74:77]
	v_mfma_f32_16x16x32_bf16 v[78:81], v[222:225], v[126:129], v[78:81]
	ds_read_b128 v[218:221], v238 offset:6912
	s_waitcnt lgkmcnt(3)
	v_mfma_f32_16x16x32_bf16 v[2:5], v[226:229], v[150:153], v[2:5]
	v_mfma_f32_16x16x32_bf16 v[6:9], v[226:229], v[154:157], v[6:9]
	ds_read_b128 v[222:225], v238 offset:9216
	s_waitcnt lgkmcnt(3)
	v_mfma_f32_16x16x32_bf16 v[10:13], v[230:233], v[150:153], v[10:13]
	v_mfma_f32_16x16x32_bf16 v[14:17], v[230:233], v[154:157], v[14:17]
	ds_read_b128 v[226:229], v238 offset:11520
	s_waitcnt lgkmcnt(3)
	v_mfma_f32_16x16x32_bf16 v[18:21], v[234:237], v[150:153], v[18:21]
	v_mfma_f32_16x16x32_bf16 v[22:25], v[234:237], v[154:157], v[22:25]
	ds_read_b128 v[230:233], v238 offset:13824
	s_waitcnt lgkmcnt(3)
	v_mfma_f32_16x16x32_bf16 v[26:29], v[218:221], v[150:153], v[26:29]
	v_mfma_f32_16x16x32_bf16 v[30:33], v[218:221], v[154:157], v[30:33]
	ds_read_b128 v[234:237], v238 offset:16128
	s_waitcnt lgkmcnt(3)
	v_mfma_f32_16x16x32_bf16 v[34:37], v[222:225], v[150:153], v[34:37]
	v_mfma_f32_16x16x32_bf16 v[38:41], v[222:225], v[154:157], v[38:41]
	s_waitcnt lgkmcnt(2)
	v_mfma_f32_16x16x32_bf16 v[42:45], v[226:229], v[150:153], v[42:45]
	v_mfma_f32_16x16x32_bf16 v[46:49], v[226:229], v[154:157], v[46:49]
	s_waitcnt lgkmcnt(1)
	v_mfma_f32_16x16x32_bf16 v[50:53], v[230:233], v[150:153], v[50:53]
	v_mfma_f32_16x16x32_bf16 v[54:57], v[230:233], v[154:157], v[54:57]
	s_waitcnt lgkmcnt(0)
	v_mfma_f32_16x16x32_bf16 v[58:61], v[234:237], v[150:153], v[58:61]
	v_mfma_f32_16x16x32_bf16 v[62:65], v[234:237], v[154:157], v[62:65]
	s_add_i32 s13, s91, 31
	s_cmp_gt_i32 s13, s12
	s_cbranch_scc1 .Lv3_h0_mask
.Lv3_h0_sm:
	s_cmp_eq_u32 s21, 0
	s_cbranch_scc1 .Lv3_h0_grow
	v_max3_f32 v207, v66, v67, v68
	v_max3_f32 v239, v74, v75, v76
	v_max3_f32 v207, v207, v69, v70
	v_max3_f32 v239, v239, v77, v78
	v_max3_f32 v207, v207, v71, v72
	v_max3_f32 v239, v239, v79, v80
	v_max3_f32 v207, v207, v73, v81
	v_max_f32_e32 v207, v207, v239
	v_cmp_lt_f32_e32 vcc, 0x41000000, v207
	s_cbranch_vccnz .Lv3_h0_grow
.Lv3_h0_exp:
	v_exp_f32_e32 v66, v66
	v_exp_f32_e32 v67, v67
	v_exp_f32_e32 v68, v68
	v_exp_f32_e32 v69, v69
	v_exp_f32_e32 v70, v70
	v_exp_f32_e32 v71, v71
	v_exp_f32_e32 v72, v72
	v_exp_f32_e32 v73, v73
	v_exp_f32_e32 v74, v74
	v_exp_f32_e32 v75, v75
	v_exp_f32_e32 v76, v76
	v_exp_f32_e32 v77, v77
	v_exp_f32_e32 v78, v78
	v_exp_f32_e32 v79, v79
	v_exp_f32_e32 v80, v80
	v_exp_f32_e32 v81, v81
	v_add_f32_e32 v199, v199, v66
	v_add_f32_e32 v203, v203, v70
	v_add_f32_e32 v199, v199, v74
	v_add_f32_e32 v203, v203, v78
	v_add_f32_e32 v199, v199, v67
	v_add_f32_e32 v203, v203, v71
	v_add_f32_e32 v199, v199, v75
	v_add_f32_e32 v203, v203, v79
	v_add_f32_e32 v199, v199, v68
	v_add_f32_e32 v203, v203, v72
	v_add_f32_e32 v199, v199, v76
	v_add_f32_e32 v203, v203, v80
	v_add_f32_e32 v199, v199, v69
	v_add_f32_e32 v203, v203, v73
	v_add_f32_e32 v199, v199, v77
	v_add_f32_e32 v203, v203, v81
	v_cvt_pk_bf16_f32 v150, v66, v67
	v_cvt_pk_bf16_f32 v151, v68, v69
	v_cvt_pk_bf16_f32 v152, v74, v75
	v_cvt_pk_bf16_f32 v153, v76, v77
	v_cvt_pk_bf16_f32 v154, v70, v71
	v_cvt_pk_bf16_f32 v155, v72, v73
	v_cvt_pk_bf16_f32 v156, v78, v79
	v_cvt_pk_bf16_f32 v157, v80, v81
.Lv3_h0_end:
.Lv3_h1:
	s_add_i32 s91, s54, 32
	s_add_i32 s13, s12, 63
	s_cmp_le_i32 s91, s13
	s_cbranch_scc0 .Lv3_h1_end
	v_add_u32_e32 v205, 0x3200, v204
	v_add_u32_e32 v238, v209, v200
	s_add_i32 s4, s89, 0xc840
	ds_read_b128 v[218:221], v205
	ds_read_b128 v[222:225], v205 offset:3200
	ds_read_b128 v[226:229], v205 offset:64
	ds_read_b128 v[230:233], v205 offset:3264
	v_mov_b32_e32 v209, s4
	s_waitcnt lgkmcnt(3)
	v_mfma_f32_16x16x32_bf16 v[66:69], v[218:221], v[82:85], v[210:213]
	v_mfma_f32_16x16x32_bf16 v[70:73], v[218:221], v[106:109], v[214:217]
	ds_read_b128 v[234:237], v205 offset:128
	s_waitcnt lgkmcnt(3)
	v_mfma_f32_16x16x32_bf16 v[74:77], v[222:225], v[82:85], v[210:213]
	v_mfma_f32_16x16x32_bf16 v[78:81], v[222:225], v[106:109], v[214:217]
	ds_read_b128 v[218:221], v205 offset:3328
	s_waitcnt lgkmcnt(3)
	v_mfma_f32_16x16x32_bf16 v[66:69], v[226:229], v[86:89], v[66:69]
	v_mfma_f32_16x16x32_bf16 v[70:73], v[226:229], v[110:113], v[70:73]
	ds_read_b128 v[222:225], v205 offset:192
	s_waitcnt lgkmcnt(3)
	v_mfma_f32_16x16x32_bf16 v[74:77], v[230:233], v[86:89], v[74:77]
	v_mfma_f32_16x16x32_bf16 v[78:81], v[230:233], v[110:113], v[78:81]
	ds_read_b128 v[226:229], v205 offset:3392
	s_waitcnt lgkmcnt(3)
	v_mfma_f32_16x16x32_bf16 v[66:69], v[234:237], v[90:93], v[66:69]
	v_mfma_f32_16x16x32_bf16 v[70:73], v[234:237], v[114:117], v[70:73]
	ds_read_b128 v[230:233], v205 offset:256
	s_waitcnt lgkmcnt(3)
	v_mfma_f32_16x16x32_bf16 v[74:77], v[218:221], v[90:93], v[74:77]
	v_mfma_f32_16x16x32_bf16 v[78:81], v[218:221], v[114:117], v[78:81]
	ds_read_b128 v[234:237], v205 offset:3456
	s_waitcnt lgkmcnt(3)
	v_mfma_f32_16x16x32_bf16 v[66:69], v[222:225], v[94:97], v[66:69]
	v_mfma_f32_16x16x32_bf16 v[70:73], v[222:225], v[118:121], v[70:73]
	ds_read_b128 v[218:221], v205 offset:320
	s_waitcnt lgkmcnt(3)
	v_mfma_f32_16x16x32_bf16 v[74:77], v[226:229], v[94:97], v[74:77]
	v_mfma_f32_16x16x32_bf16 v[78:81], v[226:229], v[118:121], v[78:81]
	ds_read_b128 v[222:225], v205 offset:3520
	s_waitcnt lgkmcnt(3)
	v_mfma_f32_16x16x32_bf16 v[66:69], v[230:233], v[98:101], v[66:69]
	v_mfma_f32_16x16x32_bf16 v[70:73], v[230:233], v[122:125], v[70:73]
	ds_read_b128 v[226:229], v238
	s_waitcnt lgkmcnt(3)
	v_mfma_f32_16x16x32_bf16 v[74:77], v[234:237], v[98:101], v[74:77]
	v_mfma_f32_16x16x32_bf16 v[78:81], v[234:237], v[122:125], v[78:81]
	ds_read_b128 v[230:233], v238 offset:2304
	s_waitcnt lgkmcnt(3)
	v_mfma_f32_16x16x32_bf16 v[66:69], v[218:221], v[102:105], v[66:69]
	v_mfma_f32_16x16x32_bf16 v[70:73], v[218:221], v[126:129], v[70:73]
	ds_read_b128 v[234:237], v238 offset:4608
	s_waitcnt lgkmcnt(3)
	v_mfma_f32_16x16x32_bf16 v[74:77], v[222:225], v[102:105], v[74:77]
	v_mfma_f32_16x16x32_bf16 v[78:81], v[222:225], v[126:129], v[78:81]
	ds_read_b128 v[218:221], v238 offset:6912
	s_waitcnt lgkmcnt(3)
	v_mfma_f32_16x16x32_bf16 v[2:5], v[226:229], v[150:153], v[2:5]
	v_mfma_f32_16x16x32_bf16 v[6:9], v[226:229], v[154:157], v[6:9]
	ds_read_b128 v[222:225], v238 offset:9216
	s_waitcnt lgkmcnt(3)
	v_mfma_f32_16x16x32_bf16 v[10:13], v[230:233], v[150:153], v[10:13]
	v_mfma_f32_16x16x32_bf16 v[14:17], v[230:233], v[154:157], v[14:17]
	ds_read_b128 v[226:229], v238 offset:11520
	s_waitcnt lgkmcnt(3)
	v_mfma_f32_16x16x32_bf16 v[18:21], v[234:237], v[150:153], v[18:21]
	v_mfma_f32_16x16x32_bf16 v[22:25], v[234:237], v[154:157], v[22:25]
	ds_read_b128 v[230:233], v238 offset:13824
	s_waitcnt lgkmcnt(3)
	v_mfma_f32_16x16x32_bf16 v[26:29], v[218:221], v[150:153], v[26:29]
	v_mfma_f32_16x16x32_bf16 v[30:33], v[218:221], v[154:157], v[30:33]
	ds_read_b128 v[234:237], v238 offset:16128
	s_waitcnt lgkmcnt(3)
	v_mfma_f32_16x16x32_bf16 v[34:37], v[222:225], v[150:153], v[34:37]
	v_mfma_f32_16x16x32_bf16 v[38:41], v[222:225], v[154:157], v[38:41]
	s_waitcnt lgkmcnt(2)
	v_mfma_f32_16x16x32_bf16 v[42:45], v[226:229], v[150:153], v[42:45]
	v_mfma_f32_16x16x32_bf16 v[46:49], v[226:229], v[154:157], v[46:49]
	s_waitcnt lgkmcnt(1)
	v_mfma_f32_16x16x32_bf16 v[50:53], v[230:233], v[150:153], v[50:53]
	v_mfma_f32_16x16x32_bf16 v[54:57], v[230:233], v[154:157], v[54:57]
	s_waitcnt lgkmcnt(0)
	v_mfma_f32_16x16x32_bf16 v[58:61], v[234:237], v[150:153], v[58:61]
	v_mfma_f32_16x16x32_bf16 v[62:65], v[234:237], v[154:157], v[62:65]
	s_add_i32 s13, s91, 31
	s_cmp_gt_i32 s13, s12
	s_cbranch_scc1 .Lv3_h1_mask

.Lv3_h1_end:
	s_branch .LBB0_776
.Lv3_h0_mask:
	s_sub_i32 s13, s12, s91
	s_sub_i32 s14, s13, 0
	v_cmp_ge_i32_e32 vcc, s14, v197
	s_nop 1
	v_cndmask_b32_e32 v66, v184, v66, vcc
	s_sub_i32 s14, s13, 1
	v_cmp_ge_i32_e32 vcc, s14, v197
	s_nop 1
	v_cndmask_b32_e32 v67, v184, v67, vcc
	s_sub_i32 s14, s13, 2
	v_cmp_ge_i32_e32 vcc, s14, v197
	s_nop 1
	v_cndmask_b32_e32 v68, v184, v68, vcc
	s_sub_i32 s14, s13, 3
	v_cmp_ge_i32_e32 vcc, s14, v197
	s_nop 1
	v_cndmask_b32_e32 v69, v184, v69, vcc
	s_add_i32 s14, s13, 16
	v_cmp_ge_i32_e32 vcc, s14, v197
	s_nop 1
	v_cndmask_b32_e32 v70, v184, v70, vcc
	s_add_i32 s14, s13, 15
	v_cmp_ge_i32_e32 vcc, s14, v197
	s_nop 1
	v_cndmask_b32_e32 v71, v184, v71, vcc
	s_add_i32 s14, s13, 14
	v_cmp_ge_i32_e32 vcc, s14, v197
	s_nop 1
	v_cndmask_b32_e32 v72, v184, v72, vcc
	s_add_i32 s14, s13, 13
	v_cmp_ge_i32_e32 vcc, s14, v197
	s_nop 1
	v_cndmask_b32_e32 v73, v184, v73, vcc
	s_sub_i32 s14, s13, 8
	v_cmp_ge_i32_e32 vcc, s14, v197
	s_nop 1
	v_cndmask_b32_e32 v74, v184, v74, vcc
	s_sub_i32 s14, s13, 9
	v_cmp_ge_i32_e32 vcc, s14, v197
	s_nop 1
	v_cndmask_b32_e32 v75, v184, v75, vcc
	s_sub_i32 s14, s13, 10
	v_cmp_ge_i32_e32 vcc, s14, v197
	s_nop 1
	v_cndmask_b32_e32 v76, v184, v76, vcc
	s_sub_i32 s14, s13, 11
	v_cmp_ge_i32_e32 vcc, s14, v197
	s_nop 1
	v_cndmask_b32_e32 v77, v184, v77, vcc
	s_add_i32 s14, s13, 8
	v_cmp_ge_i32_e32 vcc, s14, v197
	s_nop 1
	v_cndmask_b32_e32 v78, v184, v78, vcc
	s_add_i32 s14, s13, 7
	v_cmp_ge_i32_e32 vcc, s14, v197
	s_nop 1
	v_cndmask_b32_e32 v79, v184, v79, vcc
	s_add_i32 s14, s13, 6
	v_cmp_ge_i32_e32 vcc, s14, v197
	s_nop 1
	v_cndmask_b32_e32 v80, v184, v80, vcc
	s_add_i32 s14, s13, 5
	v_cmp_ge_i32_e32 vcc, s14, v197
	s_nop 1
	v_cndmask_b32_e32 v81, v184, v81, vcc
	s_branch .Lv3_h0_sm
.Lv3_h0_grow:
	v_max3_f32 v239, v66, v67, v68
	v_max3_f32 v239, v239, v69, v74
	v_max3_f32 v239, v239, v75, v76
	v_max_f32_e32 v239, v239, v77
	v_max3_f32 v244, v70, v71, v72
	v_max3_f32 v244, v244, v73, v78
	v_max3_f32 v244, v244, v79, v80
	v_max_f32_e32 v244, v244, v81
	ds_bpermute_b32 v245, v208, v239
	ds_bpermute_b32 v247, v208, v244
	s_waitcnt lgkmcnt(0)
	v_max_f32_e32 v239, v239, v245
	v_max_f32_e32 v244, v244, v247
	ds_bpermute_b32 v245, v198, v239
	ds_bpermute_b32 v247, v198, v244
	s_waitcnt lgkmcnt(0)
	v_max_f32_e32 v239, v239, v245
	v_max_f32_e32 v244, v244, v247
	s_cmp_eq_u32 s21, 0
	s_cbranch_scc1 .Lv3_h0_ginit
	v_max_f32_e32 v239, 0, v239
	v_max_f32_e32 v244, 0, v244
	v_sub_f32_e32 v240, 0, v239
	v_sub_f32_e32 v242, 0, v244
	v_exp_f32_e32 v240, v240
	v_exp_f32_e32 v242, v242
	s_nop 0
	v_mul_f32_e32 v199, v199, v240
	v_mul_f32_e32 v203, v203, v242
	v_pk_mul_f32 v[2:3], v[2:3], v[240:241] op_sel_hi:[1,0]
	v_pk_mul_f32 v[4:5], v[4:5], v[240:241] op_sel_hi:[1,0]
	v_pk_mul_f32 v[6:7], v[6:7], v[242:243] op_sel_hi:[1,0]
	v_pk_mul_f32 v[8:9], v[8:9], v[242:243] op_sel_hi:[1,0]
	v_pk_mul_f32 v[10:11], v[10:11], v[240:241] op_sel_hi:[1,0]
	v_pk_mul_f32 v[12:13], v[12:13], v[240:241] op_sel_hi:[1,0]
	v_pk_mul_f32 v[14:15], v[14:15], v[242:243] op_sel_hi:[1,0]
	v_pk_mul_f32 v[16:17], v[16:17], v[242:243] op_sel_hi:[1,0]
	v_pk_mul_f32 v[18:19], v[18:19], v[240:241] op_sel_hi:[1,0]
	v_pk_mul_f32 v[20:21], v[20:21], v[240:241] op_sel_hi:[1,0]
	v_pk_mul_f32 v[22:23], v[22:23], v[242:243] op_sel_hi:[1,0]
	v_pk_mul_f32 v[24:25], v[24:25], v[242:243] op_sel_hi:[1,0]
	v_pk_mul_f32 v[26:27], v[26:27], v[240:241] op_sel_hi:[1,0]
	v_pk_mul_f32 v[28:29], v[28:29], v[240:241] op_sel_hi:[1,0]
	v_pk_mul_f32 v[30:31], v[30:31], v[242:243] op_sel_hi:[1,0]
	v_pk_mul_f32 v[32:33], v[32:33], v[242:243] op_sel_hi:[1,0]
	v_pk_mul_f32 v[34:35], v[34:35], v[240:241] op_sel_hi:[1,0]
	v_pk_mul_f32 v[36:37], v[36:37], v[240:241] op_sel_hi:[1,0]
	v_pk_mul_f32 v[38:39], v[38:39], v[242:243] op_sel_hi:[1,0]
	v_pk_mul_f32 v[40:41], v[40:41], v[242:243] op_sel_hi:[1,0]
	v_pk_mul_f32 v[42:43], v[42:43], v[240:241] op_sel_hi:[1,0]
	v_pk_mul_f32 v[44:45], v[44:45], v[240:241] op_sel_hi:[1,0]
	v_pk_mul_f32 v[46:47], v[46:47], v[242:243] op_sel_hi:[1,0]
	v_pk_mul_f32 v[48:49], v[48:49], v[242:243] op_sel_hi:[1,0]
	v_pk_mul_f32 v[50:51], v[50:51], v[240:241] op_sel_hi:[1,0]
	v_pk_mul_f32 v[52:53], v[52:53], v[240:241] op_sel_hi:[1,0]
	v_pk_mul_f32 v[54:55], v[54:55], v[242:243] op_sel_hi:[1,0]
	v_pk_mul_f32 v[56:57], v[56:57], v[242:243] op_sel_hi:[1,0]
	v_pk_mul_f32 v[58:59], v[58:59], v[240:241] op_sel_hi:[1,0]
	v_pk_mul_f32 v[60:61], v[60:61], v[240:241] op_sel_hi:[1,0]
	v_pk_mul_f32 v[62:63], v[62:63], v[242:243] op_sel_hi:[1,0]
	v_pk_mul_f32 v[64:65], v[64:65], v[242:243] op_sel_hi:[1,0]
.Lv3_h0_ginit:
	s_mov_b32 s21, 1
	v_add_f32_e32 v206, v206, v239
	v_add_f32_e32 v201, v201, v244
	v_sub_f32_e32 v210, 0, v206
	v_sub_f32_e32 v214, 0, v201
	v_sub_f32_e32 v211, 0, v206
	v_sub_f32_e32 v215, 0, v201
	v_sub_f32_e32 v212, 0, v206
	v_sub_f32_e32 v216, 0, v201
	v_sub_f32_e32 v213, 0, v206
	v_sub_f32_e32 v217, 0, v201
	v_sub_f32_e32 v66, v66, v239
	v_sub_f32_e32 v70, v70, v244
	v_sub_f32_e32 v67, v67, v239
	v_sub_f32_e32 v71, v71, v244
	v_sub_f32_e32 v68, v68, v239
	v_sub_f32_e32 v72, v72, v244
	v_sub_f32_e32 v69, v69, v239
	v_sub_f32_e32 v73, v73, v244
	v_sub_f32_e32 v74, v74, v239
	v_sub_f32_e32 v78, v78, v244
	v_sub_f32_e32 v75, v75, v239
	v_sub_f32_e32 v79, v79, v244
	v_sub_f32_e32 v76, v76, v239
	v_sub_f32_e32 v80, v80, v244
	v_sub_f32_e32 v77, v77, v239
	v_sub_f32_e32 v81, v81, v244
	s_branch .Lv3_h0_exp
